# in-GEMM side-job k-loops: 16 fragment loads in flight per 4x-unrolled iteration with counted vmcnt (was load-wait-MFMA per k-step)
# speedup vs baseline: 1.1838x; 1.0097x over previous
.LBB0_254:
	v_lshl_add_u64 v[34:35], v[26:27], 0, v[16:17]
	v_add_co_u32_e32 v52, vcc, s12, v34
	v_lshl_add_u64 v[56:57], v[28:29], 0, v[16:17]
	s_nop 0
	v_addc_co_u32_e32 v53, vcc, 0, v35, vcc
	v_add_co_u32_e32 v54, vcc, s13, v34
	global_load_dwordx4 v[30:33], v[52:53], off
	s_nop 0
	v_addc_co_u32_e32 v55, vcc, 0, v35, vcc
	global_load_dwordx4 v[34:37], v[54:55], off
	v_add_co_u32_e32 v58, vcc, s14, v56
	global_load_dwordx4 v[38:41], v[56:57], off
	s_nop 0
	v_addc_co_u32_e32 v59, vcc, 0, v57, vcc
	global_load_dwordx4 v[48:51], v[58:59], off
	global_load_dwordx4 v[76:79], v[52:53], off offset:128
	global_load_dwordx4 v[80:83], v[54:55], off offset:128
	global_load_dwordx4 v[84:87], v[56:57], off offset:128
	global_load_dwordx4 v[88:91], v[58:59], off offset:128
	global_load_dwordx4 v[92:95], v[52:53], off offset:256
	global_load_dwordx4 v[96:99], v[54:55], off offset:256
	global_load_dwordx4 v[100:103], v[56:57], off offset:256
	global_load_dwordx4 v[104:107], v[58:59], off offset:256
	global_load_dwordx4 v[108:111], v[52:53], off offset:384
	global_load_dwordx4 v[112:115], v[54:55], off offset:384
	global_load_dwordx4 v[116:119], v[56:57], off offset:384
	global_load_dwordx4 v[120:123], v[58:59], off offset:384
	s_addk_i32 s4, 0x80
	v_lshl_add_u64 v[28:29], v[28:29], 0, s[6:7]
	v_lshl_add_u64 v[26:27], v[26:27], 0, s[6:7]
	s_cmpk_lt_u32 s4, 0x3e0
	s_waitcnt vmcnt(12)
	v_mfma_f32_16x16x32_bf16 v[12:15], v[30:33], v[38:41], v[12:15]
	v_mfma_f32_16x16x32_bf16 v[8:11], v[30:33], v[48:51], v[8:11]
	v_mfma_f32_16x16x32_bf16 v[4:7], v[34:37], v[38:41], v[4:7]
	v_mfma_f32_16x16x32_bf16 v[0:3], v[34:37], v[48:51], v[0:3]
	s_waitcnt vmcnt(8)
	v_mfma_f32_16x16x32_bf16 v[12:15], v[76:79], v[84:87], v[12:15]
	v_mfma_f32_16x16x32_bf16 v[8:11], v[76:79], v[88:91], v[8:11]
	v_mfma_f32_16x16x32_bf16 v[4:7], v[80:83], v[84:87], v[4:7]
	v_mfma_f32_16x16x32_bf16 v[0:3], v[80:83], v[88:91], v[0:3]
	s_waitcnt vmcnt(4)
	v_mfma_f32_16x16x32_bf16 v[12:15], v[92:95], v[100:103], v[12:15]
	v_mfma_f32_16x16x32_bf16 v[8:11], v[92:95], v[104:107], v[8:11]
	v_mfma_f32_16x16x32_bf16 v[4:7], v[96:99], v[100:103], v[4:7]
	v_mfma_f32_16x16x32_bf16 v[0:3], v[96:99], v[104:107], v[0:3]
	s_waitcnt vmcnt(0)
	v_mfma_f32_16x16x32_bf16 v[12:15], v[108:111], v[116:119], v[12:15]
	v_mfma_f32_16x16x32_bf16 v[8:11], v[108:111], v[120:123], v[8:11]
	v_mfma_f32_16x16x32_bf16 v[4:7], v[112:115], v[116:119], v[4:7]
	v_mfma_f32_16x16x32_bf16 v[0:3], v[112:115], v[120:123], v[0:3]
	s_cbranch_scc1 .LBB0_254
	s_mov_b64 s[4:5], 0

.LBB0_258:
	v_lshl_add_u64 v[30:31], v[24:25], 0, v[16:17]
	v_add_co_u32_e32 v48, vcc, s12, v30
	v_lshl_add_u64 v[52:53], v[22:23], 0, v[16:17]
	s_nop 0
	v_addc_co_u32_e32 v49, vcc, 0, v31, vcc
	v_add_co_u32_e32 v50, vcc, s13, v30
	global_load_dwordx4 v[34:37], v[52:53], off
	s_nop 0
	v_addc_co_u32_e32 v51, vcc, 0, v31, vcc
	v_add_co_u32_e32 v54, vcc, s14, v52
	global_load_dwordx4 v[26:29], v[48:49], off
	global_load_dwordx4 v[30:33], v[50:51], off
	v_addc_co_u32_e32 v55, vcc, 0, v53, vcc
	global_load_dwordx4 v[38:41], v[54:55], off
	global_load_dwordx4 v[80:83], v[48:49], off offset:128
	global_load_dwordx4 v[84:87], v[50:51], off offset:128
	global_load_dwordx4 v[76:79], v[52:53], off offset:128
	global_load_dwordx4 v[88:91], v[54:55], off offset:128
	global_load_dwordx4 v[96:99], v[48:49], off offset:256
	global_load_dwordx4 v[100:103], v[50:51], off offset:256
	global_load_dwordx4 v[92:95], v[52:53], off offset:256
	global_load_dwordx4 v[104:107], v[54:55], off offset:256
	global_load_dwordx4 v[112:115], v[48:49], off offset:384
	global_load_dwordx4 v[116:119], v[50:51], off offset:384
	global_load_dwordx4 v[108:111], v[52:53], off offset:384
	global_load_dwordx4 v[120:123], v[54:55], off offset:384
	s_addk_i32 s4, 0x80
	v_lshl_add_u64 v[22:23], v[22:23], 0, s[6:7]
	v_lshl_add_u64 v[24:25], v[24:25], 0, s[6:7]
	s_cmpk_gt_u32 s4, 0x3df
	s_waitcnt vmcnt(12)
	v_mfma_f32_16x16x32_bf16 v[12:15], v[34:37], v[26:29], v[12:15]
	v_mfma_f32_16x16x32_bf16 v[8:11], v[38:41], v[26:29], v[8:11]
	v_mfma_f32_16x16x32_bf16 v[4:7], v[34:37], v[30:33], v[4:7]
	v_mfma_f32_16x16x32_bf16 v[0:3], v[38:41], v[30:33], v[0:3]
	s_waitcnt vmcnt(8)
	v_mfma_f32_16x16x32_bf16 v[12:15], v[76:79], v[80:83], v[12:15]
	v_mfma_f32_16x16x32_bf16 v[8:11], v[88:91], v[80:83], v[8:11]
	v_mfma_f32_16x16x32_bf16 v[4:7], v[76:79], v[84:87], v[4:7]
	v_mfma_f32_16x16x32_bf16 v[0:3], v[88:91], v[84:87], v[0:3]
	s_waitcnt vmcnt(4)
	v_mfma_f32_16x16x32_bf16 v[12:15], v[92:95], v[96:99], v[12:15]
	v_mfma_f32_16x16x32_bf16 v[8:11], v[104:107], v[96:99], v[8:11]
	v_mfma_f32_16x16x32_bf16 v[4:7], v[92:95], v[100:103], v[4:7]
	v_mfma_f32_16x16x32_bf16 v[0:3], v[104:107], v[100:103], v[0:3]
	s_waitcnt vmcnt(0)
	v_mfma_f32_16x16x32_bf16 v[12:15], v[108:111], v[112:115], v[12:15]
	v_mfma_f32_16x16x32_bf16 v[8:11], v[120:123], v[112:115], v[8:11]
	v_mfma_f32_16x16x32_bf16 v[4:7], v[108:111], v[116:119], v[4:7]
	v_mfma_f32_16x16x32_bf16 v[0:3], v[120:123], v[116:119], v[0:3]
	s_cbranch_scc0 .LBB0_258

.LBB0_893:
	v_lshl_add_u64 v[36:37], v[28:29], 0, v[20:21]
	s_mov_b32 s9, 0x12d0000
	v_add_co_u32_e32 v48, vcc, s9, v36
	s_mov_b32 s9, 0x12d8000
	s_nop 0
	v_addc_co_u32_e32 v49, vcc, 0, v37, vcc
	v_add_co_u32_e32 v50, vcc, s9, v36
	v_lshl_add_u64 v[52:53], v[26:27], 0, v[20:21]
	s_nop 0
	v_addc_co_u32_e32 v51, vcc, 0, v37, vcc
	s_mov_b32 s9, 0x8000
	v_add_co_u32_e32 v54, vcc, s9, v52
	global_load_dwordx4 v[40:43], v[52:53], off
	s_nop 0
	v_addc_co_u32_e32 v55, vcc, 0, v53, vcc
	global_load_dwordx4 v[44:47], v[54:55], off
	global_load_dwordx4 v[32:35], v[48:49], off
	global_load_dwordx4 v[36:39], v[50:51], off
	global_load_dwordx4 v[84:87], v[48:49], off offset:128
	global_load_dwordx4 v[88:91], v[50:51], off offset:128
	global_load_dwordx4 v[76:79], v[52:53], off offset:128
	global_load_dwordx4 v[80:83], v[54:55], off offset:128
	global_load_dwordx4 v[100:103], v[48:49], off offset:256
	global_load_dwordx4 v[104:107], v[50:51], off offset:256
	global_load_dwordx4 v[92:95], v[52:53], off offset:256
	global_load_dwordx4 v[96:99], v[54:55], off offset:256
	global_load_dwordx4 v[116:119], v[48:49], off offset:384
	global_load_dwordx4 v[120:123], v[50:51], off offset:384
	global_load_dwordx4 v[108:111], v[52:53], off offset:384
	global_load_dwordx4 v[112:115], v[54:55], off offset:384
	s_addk_i32 s8, 0x80
	v_lshl_add_u64 v[26:27], v[26:27], 0, s[0:1]
	v_lshl_add_u64 v[28:29], v[28:29], 0, s[0:1]
	s_cmpk_gt_u32 s8, 0x3df
	s_waitcnt vmcnt(12)
	v_mfma_f32_16x16x32_bf16 v[12:15], v[40:43], v[32:35], v[12:15]
	v_mfma_f32_16x16x32_bf16 v[8:11], v[44:47], v[32:35], v[8:11]
	v_mfma_f32_16x16x32_bf16 v[4:7], v[40:43], v[36:39], v[4:7]
	v_mfma_f32_16x16x32_bf16 v[0:3], v[44:47], v[36:39], v[0:3]
	s_waitcnt vmcnt(8)
	v_mfma_f32_16x16x32_bf16 v[12:15], v[76:79], v[84:87], v[12:15]
	v_mfma_f32_16x16x32_bf16 v[8:11], v[80:83], v[84:87], v[8:11]
	v_mfma_f32_16x16x32_bf16 v[4:7], v[76:79], v[88:91], v[4:7]
	v_mfma_f32_16x16x32_bf16 v[0:3], v[80:83], v[88:91], v[0:3]
	s_waitcnt vmcnt(4)
	v_mfma_f32_16x16x32_bf16 v[12:15], v[92:95], v[100:103], v[12:15]
	v_mfma_f32_16x16x32_bf16 v[8:11], v[96:99], v[100:103], v[8:11]
	v_mfma_f32_16x16x32_bf16 v[4:7], v[92:95], v[104:107], v[4:7]
	v_mfma_f32_16x16x32_bf16 v[0:3], v[96:99], v[104:107], v[0:3]
	s_waitcnt vmcnt(0)
	v_mfma_f32_16x16x32_bf16 v[12:15], v[108:111], v[116:119], v[12:15]
	v_mfma_f32_16x16x32_bf16 v[8:11], v[112:115], v[116:119], v[8:11]
	v_mfma_f32_16x16x32_bf16 v[4:7], v[108:111], v[120:123], v[4:7]
	v_mfma_f32_16x16x32_bf16 v[0:3], v[112:115], v[120:123], v[0:3]
	s_cbranch_scc0 .LBB0_893
	v_lshl_or_b32 v26, s7, 5, v30
	v_ashrrev_i32_e32 v27, 31, v26
	v_lshl_add_u64 v[28:29], v[26:27], 1, s[94:95]
	v_mov_b32_e32 v27, v21
	v_lshl_add_u64 v[32:33], v[26:27], 1, s[40:41]
	s_nop 0
	v_and_b32_sdwa v27, v12, v31 dst_sel:DWORD dst_unused:UNUSED_PAD src0_sel:WORD_1 src1_sel:DWORD
	v_add3_u32 v12, v12, v27, s6
	v_and_b32_sdwa v27, v13, v31 dst_sel:DWORD dst_unused:UNUSED_PAD src0_sel:WORD_1 src1_sel:DWORD
	v_lshl_add_u64 v[32:33], v[32:33], 0, s[2:3]
	v_cmp_gt_i32_e32 vcc, s5, v26
	s_nop 0
	v_add3_u32 v13, v13, v27, s6
	v_cndmask_b32_e32 v29, v33, v29, vcc
	v_cndmask_b32_e32 v28, v32, v28, vcc
	s_nop 0
	v_and_b32_e32 v23, 0xffff0000, v13
	v_lshl_add_u64 v[32:33], v[28:29], 0, v[16:17]
	v_cvt_pk_bf16_f32 v13, v14, v15
	v_or_b32_sdwa v12, v23, v12 dst_sel:DWORD dst_unused:UNUSED_PAD src0_sel:DWORD src1_sel:WORD_1
	global_store_dwordx2 v[32:33], v[12:13], off
	v_or_b32_e32 v12, 16, v26
	v_ashrrev_i32_e32 v13, 31, v12
	v_lshl_add_u64 v[14:15], v[12:13], 1, s[94:95]
	v_mov_b32_e32 v13, v21
	v_lshl_add_u64 v[26:27], v[12:13], 1, s[40:41]
	v_lshl_add_u64 v[26:27], v[26:27], 0, s[2:3]
	v_cmp_gt_i32_e32 vcc, s5, v12
	s_nop 1
	v_cndmask_b32_e32 v12, v26, v14, vcc
	v_and_b32_sdwa v26, v8, v31 dst_sel:DWORD dst_unused:UNUSED_PAD src0_sel:WORD_1 src1_sel:DWORD
	s_nop 0
	v_add3_u32 v8, v8, v26, s6
	v_and_b32_sdwa v26, v9, v31 dst_sel:DWORD dst_unused:UNUSED_PAD src0_sel:WORD_1 src1_sel:DWORD
	v_add3_u32 v9, v9, v26, s6
	v_and_b32_e32 v23, 0xffff0000, v9
	v_cvt_pk_bf16_f32 v9, v10, v11
	v_and_b32_sdwa v11, v4, v31 dst_sel:DWORD dst_unused:UNUSED_PAD src0_sel:WORD_1 src1_sel:DWORD
	v_add3_u32 v4, v4, v11, s6
	v_and_b32_sdwa v11, v5, v31 dst_sel:DWORD dst_unused:UNUSED_PAD src0_sel:WORD_1 src1_sel:DWORD
	v_add3_u32 v5, v5, v11, s6
	v_and_b32_e32 v10, 0xffff0000, v5
	v_cvt_pk_bf16_f32 v5, v6, v7
	v_and_b32_sdwa v7, v0, v31 dst_sel:DWORD dst_unused:UNUSED_PAD src0_sel:WORD_1 src1_sel:DWORD
	v_cndmask_b32_e32 v13, v27, v15, vcc
	v_add3_u32 v0, v0, v7, s6
	v_and_b32_sdwa v7, v1, v31 dst_sel:DWORD dst_unused:UNUSED_PAD src0_sel:WORD_1 src1_sel:DWORD
	v_lshl_add_u64 v[14:15], v[12:13], 0, v[16:17]
	v_or_b32_sdwa v8, v23, v8 dst_sel:DWORD dst_unused:UNUSED_PAD src0_sel:DWORD src1_sel:WORD_1
	v_add3_u32 v1, v1, v7, s6
	global_store_dwordx2 v[14:15], v[8:9], off
	v_lshl_add_u64 v[8:9], v[28:29], 0, v[18:19]
	v_or_b32_sdwa v4, v10, v4 dst_sel:DWORD dst_unused:UNUSED_PAD src0_sel:DWORD src1_sel:WORD_1
	v_and_b32_e32 v6, 0xffff0000, v1
	s_add_i32 s7, s7, s86
	global_store_dwordx2 v[8:9], v[4:5], off
	v_lshl_add_u64 v[4:5], v[12:13], 0, v[18:19]
	v_cvt_pk_bf16_f32 v1, v2, v3
	v_or_b32_sdwa v0, v6, v0 dst_sel:DWORD dst_unused:UNUSED_PAD src0_sel:DWORD src1_sel:WORD_1
	s_cmpk_gt_i32 s7, 0x57
	v_add_u32_e32 v22, s4, v22
	global_store_dwordx2 v[4:5], v[0:1], off
	s_cbranch_scc0 .LBB0_892

.LBB0_1350:
	v_lshl_add_u64 v[34:35], v[26:27], 0, v[16:17]
	v_add_co_u32_e32 v52, vcc, s12, v34
	v_lshl_add_u64 v[56:57], v[28:29], 0, v[16:17]
	s_nop 0
	v_addc_co_u32_e32 v53, vcc, 0, v35, vcc
	v_add_co_u32_e32 v54, vcc, s13, v34
	global_load_dwordx4 v[30:33], v[52:53], off
	s_nop 0
	v_addc_co_u32_e32 v55, vcc, 0, v35, vcc
	global_load_dwordx4 v[34:37], v[54:55], off
	v_add_co_u32_e32 v58, vcc, s14, v56
	global_load_dwordx4 v[38:41], v[56:57], off
	s_nop 0
	v_addc_co_u32_e32 v59, vcc, 0, v57, vcc
	global_load_dwordx4 v[48:51], v[58:59], off
	global_load_dwordx4 v[76:79], v[52:53], off offset:128
	global_load_dwordx4 v[80:83], v[54:55], off offset:128
	global_load_dwordx4 v[84:87], v[56:57], off offset:128
	global_load_dwordx4 v[88:91], v[58:59], off offset:128
	global_load_dwordx4 v[92:95], v[52:53], off offset:256
	global_load_dwordx4 v[96:99], v[54:55], off offset:256
	global_load_dwordx4 v[100:103], v[56:57], off offset:256
	global_load_dwordx4 v[104:107], v[58:59], off offset:256
	global_load_dwordx4 v[108:111], v[52:53], off offset:384
	global_load_dwordx4 v[112:115], v[54:55], off offset:384
	global_load_dwordx4 v[116:119], v[56:57], off offset:384
	global_load_dwordx4 v[120:123], v[58:59], off offset:384
	s_addk_i32 s4, 0x80
	v_lshl_add_u64 v[28:29], v[28:29], 0, s[0:1]
	v_lshl_add_u64 v[26:27], v[26:27], 0, s[0:1]
	s_cmpk_lt_u32 s4, 0x3e0
	s_waitcnt vmcnt(12)
	v_mfma_f32_16x16x32_bf16 v[12:15], v[30:33], v[38:41], v[12:15]
	v_mfma_f32_16x16x32_bf16 v[8:11], v[30:33], v[48:51], v[8:11]
	v_mfma_f32_16x16x32_bf16 v[4:7], v[34:37], v[38:41], v[4:7]
	v_mfma_f32_16x16x32_bf16 v[0:3], v[34:37], v[48:51], v[0:3]
	s_waitcnt vmcnt(8)
	v_mfma_f32_16x16x32_bf16 v[12:15], v[76:79], v[84:87], v[12:15]
	v_mfma_f32_16x16x32_bf16 v[8:11], v[76:79], v[88:91], v[8:11]
	v_mfma_f32_16x16x32_bf16 v[4:7], v[80:83], v[84:87], v[4:7]
	v_mfma_f32_16x16x32_bf16 v[0:3], v[80:83], v[88:91], v[0:3]
	s_waitcnt vmcnt(4)
	v_mfma_f32_16x16x32_bf16 v[12:15], v[92:95], v[100:103], v[12:15]
	v_mfma_f32_16x16x32_bf16 v[8:11], v[92:95], v[104:107], v[8:11]
	v_mfma_f32_16x16x32_bf16 v[4:7], v[96:99], v[100:103], v[4:7]
	v_mfma_f32_16x16x32_bf16 v[0:3], v[96:99], v[104:107], v[0:3]
	s_waitcnt vmcnt(0)
	v_mfma_f32_16x16x32_bf16 v[12:15], v[108:111], v[116:119], v[12:15]
	v_mfma_f32_16x16x32_bf16 v[8:11], v[108:111], v[120:123], v[8:11]
	v_mfma_f32_16x16x32_bf16 v[4:7], v[112:115], v[116:119], v[4:7]
	v_mfma_f32_16x16x32_bf16 v[0:3], v[112:115], v[120:123], v[0:3]
	s_cbranch_scc1 .LBB0_1350
	s_mov_b64 s[4:5], 0

.LBB0_1354:
	v_lshl_add_u64 v[30:31], v[24:25], 0, v[16:17]
	v_add_co_u32_e32 v48, vcc, s12, v30
	v_lshl_add_u64 v[52:53], v[22:23], 0, v[16:17]
	s_nop 0
	v_addc_co_u32_e32 v49, vcc, 0, v31, vcc
	v_add_co_u32_e32 v50, vcc, s13, v30
	global_load_dwordx4 v[34:37], v[52:53], off
	s_nop 0
	v_addc_co_u32_e32 v51, vcc, 0, v31, vcc
	v_add_co_u32_e32 v54, vcc, s14, v52
	global_load_dwordx4 v[26:29], v[48:49], off
	global_load_dwordx4 v[30:33], v[50:51], off
	v_addc_co_u32_e32 v55, vcc, 0, v53, vcc
	global_load_dwordx4 v[38:41], v[54:55], off
	global_load_dwordx4 v[80:83], v[48:49], off offset:128
	global_load_dwordx4 v[84:87], v[50:51], off offset:128
	global_load_dwordx4 v[76:79], v[52:53], off offset:128
	global_load_dwordx4 v[88:91], v[54:55], off offset:128
	global_load_dwordx4 v[96:99], v[48:49], off offset:256
	global_load_dwordx4 v[100:103], v[50:51], off offset:256
	global_load_dwordx4 v[92:95], v[52:53], off offset:256
	global_load_dwordx4 v[104:107], v[54:55], off offset:256
	global_load_dwordx4 v[112:115], v[48:49], off offset:384
	global_load_dwordx4 v[116:119], v[50:51], off offset:384
	global_load_dwordx4 v[108:111], v[52:53], off offset:384
	global_load_dwordx4 v[120:123], v[54:55], off offset:384
	s_addk_i32 s4, 0x80
	v_lshl_add_u64 v[22:23], v[22:23], 0, s[0:1]
	v_lshl_add_u64 v[24:25], v[24:25], 0, s[0:1]
	s_cmpk_gt_u32 s4, 0x3df
	s_waitcnt vmcnt(12)
	v_mfma_f32_16x16x32_bf16 v[12:15], v[34:37], v[26:29], v[12:15]
	v_mfma_f32_16x16x32_bf16 v[8:11], v[38:41], v[26:29], v[8:11]
	v_mfma_f32_16x16x32_bf16 v[4:7], v[34:37], v[30:33], v[4:7]
	v_mfma_f32_16x16x32_bf16 v[0:3], v[38:41], v[30:33], v[0:3]
	s_waitcnt vmcnt(8)
	v_mfma_f32_16x16x32_bf16 v[12:15], v[76:79], v[80:83], v[12:15]
	v_mfma_f32_16x16x32_bf16 v[8:11], v[88:91], v[80:83], v[8:11]
	v_mfma_f32_16x16x32_bf16 v[4:7], v[76:79], v[84:87], v[4:7]
	v_mfma_f32_16x16x32_bf16 v[0:3], v[88:91], v[84:87], v[0:3]
	s_waitcnt vmcnt(4)
	v_mfma_f32_16x16x32_bf16 v[12:15], v[92:95], v[96:99], v[12:15]
	v_mfma_f32_16x16x32_bf16 v[8:11], v[104:107], v[96:99], v[8:11]
	v_mfma_f32_16x16x32_bf16 v[4:7], v[92:95], v[100:103], v[4:7]
	v_mfma_f32_16x16x32_bf16 v[0:3], v[104:107], v[100:103], v[0:3]
	s_waitcnt vmcnt(0)
	v_mfma_f32_16x16x32_bf16 v[12:15], v[108:111], v[112:115], v[12:15]
	v_mfma_f32_16x16x32_bf16 v[8:11], v[120:123], v[112:115], v[8:11]
	v_mfma_f32_16x16x32_bf16 v[4:7], v[108:111], v[116:119], v[4:7]
	v_mfma_f32_16x16x32_bf16 v[0:3], v[120:123], v[116:119], v[0:3]
	s_cbranch_scc0 .LBB0_1354
